# v46 with the plain conversion loop on 256n x 128k super-tiles (16-byte loads, 1 KB contiguous per wave and row), 2 in flight
# baseline (speedup 1.0000x reference)
.Lwf_plain:
	s_load_dword s6, s[0:1], 0x4c8
	v_and_b32_e32 v29, 63, v155
	v_lshrrev_b32_e32 v24, 6, v155
	v_lshlrev_b32_e32 v26, 4, v29
	v_lshlrev_b32_e32 v152, 3, v29
	v_readfirstlane_b32 s58, v24
	s_waitcnt lgkmcnt(0)
	s_lshl_b32 s58, s58, 4
	s_cmpk_lg_u32 s6, 0x100
	s_cbranch_scc1 .Lwf_generic
	s_mov_b32 s6, 0
	s_add_i32 s7, s92, 0x40
	s_mov_b32 s30, 2
	s_cmpk_ge_i32 s7, 0xc0
	s_cselect_b32 s30, 3, s30
	s_cmpk_ge_i32 s7, 0x140
	s_cselect_b32 s30, 4, s30
	s_cmpk_ge_i32 s7, 0x1c0
	s_cselect_b32 s30, 5, s30
	s_cmpk_ge_i32 s7, 0x240
	s_cselect_b32 s30, 6, s30
	s_cmpk_ge_i32 s7, 0x2c0
	s_cselect_b32 s30, 7, s30
	s_cmpk_ge_i32 s7, 0x340
	s_cselect_b32 s30, 8, s30
	s_cmpk_ge_i32 s7, 0x3c0
	s_cselect_b32 s30, 9, s30
	s_cmpk_ge_i32 s7, 0x440
	s_cselect_b32 s30, 10, s30
	s_cmpk_ge_i32 s7, 0x4a0
	s_cselect_b32 s30, 11, s30
	s_cmpk_ge_i32 s7, 0x500
	s_cselect_b32 s30, 12, s30
	s_cmpk_ge_i32 s7, 0x520
	s_cselect_b32 s30, 13, s30
	s_mul_i32 s59, s30, 48
	s_add_u32 s10, s0, s59
	s_addc_u32 s11, s1, 0
	s_load_dwordx2 s[50:51], s[10:11], 0x100
	s_load_dwordx2 s[52:53], s[10:11], 0x110
	s_load_dwordx2 s[90:91], s[10:11], 0x118
	s_load_dword s30, s[10:11], 0x128
	s_load_dwordx2 vcc, s[0:1], 0xf8
	s_waitcnt lgkmcnt(0)
	s_lshr_b32 s30, s30, 2
	s_sub_i32 s7, s7, s30
	s_lshr_b32 s59, s90, 7
	s_add_i32 s10, s59, -1
	s_and_b32 s10, s7, s10
	s_ff1_i32_b32 s59, s59
	s_lshr_b32 s7, s7, s59
	s_lshl_b32 s10, s10, 7
	s_add_i32 s10, s10, s58
	s_lshl_b32 s11, s7, 8
	s_mul_i32 s59, s10, s91
	s_add_i32 s59, s59, s11
	s_lshl_b32 s59, s59, 2
	s_add_u32 s50, s50, s59
	s_addc_u32 s51, s51, 0
	s_mul_i32 s59, s11, s90
	s_add_i32 s59, s59, s10
	s_lshl_b32 s59, s59, 1
	s_add_u32 s52, s52, s59
	s_addc_u32 s53, s53, 0
	s_add_u32 s52, s52, vcc_lo
	s_addc_u32 s53, s53, vcc_hi
	v_mul_u32_u24_e32 v27, s90, v152
	s_lshl_b32 s56, s90, 1
	s_lshl_b32 s91, s91, 2
	global_load_dwordx4 v[28:31], v26, s[50:51] nt
	s_add_u32 s50, s50, s91
	s_addc_u32 s51, s51, 0
	global_load_dwordx4 v[32:35], v26, s[50:51] nt
	s_add_u32 s50, s50, s91
	s_addc_u32 s51, s51, 0
	global_load_dwordx4 v[36:39], v26, s[50:51] nt
	s_add_u32 s50, s50, s91
	s_addc_u32 s51, s51, 0
	global_load_dwordx4 v[40:43], v26, s[50:51] nt
	s_add_u32 s50, s50, s91
	s_addc_u32 s51, s51, 0
	global_load_dwordx4 v[44:47], v26, s[50:51] nt
	s_add_u32 s50, s50, s91
	s_addc_u32 s51, s51, 0
	global_load_dwordx4 v[48:51], v26, s[50:51] nt
	s_add_u32 s50, s50, s91
	s_addc_u32 s51, s51, 0
	global_load_dwordx4 v[52:55], v26, s[50:51] nt
	s_add_u32 s50, s50, s91
	s_addc_u32 s51, s51, 0
	global_load_dwordx4 v[56:59], v26, s[50:51] nt
	s_add_u32 s50, s50, s91
	s_addc_u32 s51, s51, 0
	global_load_dwordx4 v[60:63], v26, s[50:51] nt
	s_add_u32 s50, s50, s91
	s_addc_u32 s51, s51, 0
	global_load_dwordx4 v[64:67], v26, s[50:51] nt
	s_add_u32 s50, s50, s91
	s_addc_u32 s51, s51, 0
	global_load_dwordx4 v[68:71], v26, s[50:51] nt
	s_add_u32 s50, s50, s91
	s_addc_u32 s51, s51, 0
	global_load_dwordx4 v[72:75], v26, s[50:51] nt
	s_add_u32 s50, s50, s91
	s_addc_u32 s51, s51, 0
	global_load_dwordx4 v[76:79], v26, s[50:51] nt
	s_add_u32 s50, s50, s91
	s_addc_u32 s51, s51, 0
	global_load_dwordx4 v[80:83], v26, s[50:51] nt
	s_add_u32 s50, s50, s91
	s_addc_u32 s51, s51, 0
	global_load_dwordx4 v[0:3], v26, s[50:51] nt
	s_add_u32 s50, s50, s91
	s_addc_u32 s51, s51, 0
	global_load_dwordx4 v[4:7], v26, s[50:51] nt
	s_add_i32 s6, s6, 1
	s_cmp_ge_u32 s6, 5
	s_cbranch_scc1 .Lwf_pdrain1
	s_lshl_b32 s7, s6, 8
	s_add_i32 s7, s7, s92
	s_addk_i32 s7, 0x40
	s_mov_b32 s30, 2
	s_cmpk_ge_i32 s7, 0xc0
	s_cselect_b32 s30, 3, s30
	s_cmpk_ge_i32 s7, 0x140
	s_cselect_b32 s30, 4, s30
	s_cmpk_ge_i32 s7, 0x1c0
	s_cselect_b32 s30, 5, s30
	s_cmpk_ge_i32 s7, 0x240
	s_cselect_b32 s30, 6, s30
	s_cmpk_ge_i32 s7, 0x2c0
	s_cselect_b32 s30, 7, s30
	s_cmpk_ge_i32 s7, 0x340
	s_cselect_b32 s30, 8, s30
	s_cmpk_ge_i32 s7, 0x3c0
	s_cselect_b32 s30, 9, s30
	s_cmpk_ge_i32 s7, 0x440
	s_cselect_b32 s30, 10, s30
	s_cmpk_ge_i32 s7, 0x4a0
	s_cselect_b32 s30, 11, s30
	s_cmpk_ge_i32 s7, 0x500
	s_cselect_b32 s30, 12, s30
	s_cmpk_ge_i32 s7, 0x520
	s_cselect_b32 s30, 13, s30
	s_mul_i32 s59, s30, 48
	s_add_u32 s10, s0, s59
	s_addc_u32 s11, s1, 0
	s_load_dwordx2 s[50:51], s[10:11], 0x100
	s_load_dwordx2 s[54:55], s[10:11], 0x110
	s_load_dwordx2 s[90:91], s[10:11], 0x118
	s_load_dword s30, s[10:11], 0x128
	s_load_dwordx2 vcc, s[0:1], 0xf8
	s_waitcnt lgkmcnt(0)
	s_lshr_b32 s30, s30, 2
	s_sub_i32 s7, s7, s30
	s_lshr_b32 s59, s90, 7
	s_add_i32 s10, s59, -1
	s_and_b32 s10, s7, s10
	s_ff1_i32_b32 s59, s59
	s_lshr_b32 s7, s7, s59
	s_lshl_b32 s10, s10, 7
	s_add_i32 s10, s10, s58
	s_lshl_b32 s11, s7, 8
	s_mul_i32 s59, s10, s91
	s_add_i32 s59, s59, s11
	s_lshl_b32 s59, s59, 2
	s_add_u32 s50, s50, s59
	s_addc_u32 s51, s51, 0
	s_mul_i32 s59, s11, s90
	s_add_i32 s59, s59, s10
	s_lshl_b32 s59, s59, 1
	s_add_u32 s54, s54, s59
	s_addc_u32 s55, s55, 0
	s_add_u32 s54, s54, vcc_lo
	s_addc_u32 s55, s55, vcc_hi
	v_mul_u32_u24_e32 v24, s90, v152
	s_lshl_b32 s57, s90, 1
	s_lshl_b32 s91, s91, 2
	global_load_dwordx4 v[86:89], v26, s[50:51] nt
	s_add_u32 s50, s50, s91
	s_addc_u32 s51, s51, 0
	global_load_dwordx4 v[90:93], v26, s[50:51] nt
	s_add_u32 s50, s50, s91
	s_addc_u32 s51, s51, 0
	global_load_dwordx4 v[94:97], v26, s[50:51] nt
	s_add_u32 s50, s50, s91
	s_addc_u32 s51, s51, 0
	global_load_dwordx4 v[98:101], v26, s[50:51] nt
	s_add_u32 s50, s50, s91
	s_addc_u32 s51, s51, 0
	global_load_dwordx4 v[102:105], v26, s[50:51] nt
	s_add_u32 s50, s50, s91
	s_addc_u32 s51, s51, 0
	global_load_dwordx4 v[106:109], v26, s[50:51] nt
	s_add_u32 s50, s50, s91
	s_addc_u32 s51, s51, 0
	global_load_dwordx4 v[110:113], v26, s[50:51] nt
	s_add_u32 s50, s50, s91
	s_addc_u32 s51, s51, 0
	global_load_dwordx4 v[114:117], v26, s[50:51] nt
	s_add_u32 s50, s50, s91
	s_addc_u32 s51, s51, 0
	global_load_dwordx4 v[118:121], v26, s[50:51] nt
	s_add_u32 s50, s50, s91
	s_addc_u32 s51, s51, 0
	global_load_dwordx4 v[122:125], v26, s[50:51] nt
	s_add_u32 s50, s50, s91
	s_addc_u32 s51, s51, 0
	global_load_dwordx4 v[126:129], v26, s[50:51] nt
	s_add_u32 s50, s50, s91
	s_addc_u32 s51, s51, 0
	global_load_dwordx4 v[130:133], v26, s[50:51] nt
	s_add_u32 s50, s50, s91
	s_addc_u32 s51, s51, 0
	global_load_dwordx4 v[134:137], v26, s[50:51] nt
	s_add_u32 s50, s50, s91
	s_addc_u32 s51, s51, 0
	global_load_dwordx4 v[140:143], v26, s[50:51] nt
	s_add_u32 s50, s50, s91
	s_addc_u32 s51, s51, 0
	global_load_dwordx4 v[144:147], v26, s[50:51] nt
	s_add_u32 s50, s50, s91
	s_addc_u32 s51, s51, 0
	global_load_dwordx4 v[148:151], v26, s[50:51] nt
.Lwf_loop:
	s_waitcnt vmcnt(16)
	v_cvt_pk_bf16_f32 v156, v28, v32
	v_cvt_pk_bf16_f32 v157, v36, v40
	v_cvt_pk_bf16_f32 v158, v44, v48
	v_cvt_pk_bf16_f32 v159, v52, v56
	v_cvt_pk_bf16_f32 v160, v60, v64
	v_cvt_pk_bf16_f32 v161, v68, v72
	v_cvt_pk_bf16_f32 v162, v76, v80
	v_cvt_pk_bf16_f32 v163, v0, v4
	global_store_dwordx4 v27, v[156:159], s[52:53]
	global_store_dwordx4 v27, v[160:163], s[52:53] offset:16
	s_add_u32 s52, s52, s56
	s_addc_u32 s53, s53, 0
	v_cvt_pk_bf16_f32 v164, v29, v33
	v_cvt_pk_bf16_f32 v165, v37, v41
	v_cvt_pk_bf16_f32 v166, v45, v49
	v_cvt_pk_bf16_f32 v167, v53, v57
	v_cvt_pk_bf16_f32 v168, v61, v65
	v_cvt_pk_bf16_f32 v169, v69, v73
	v_cvt_pk_bf16_f32 v170, v77, v81
	v_cvt_pk_bf16_f32 v171, v1, v5
	global_store_dwordx4 v27, v[164:167], s[52:53]
	global_store_dwordx4 v27, v[168:171], s[52:53] offset:16
	s_add_u32 s52, s52, s56
	s_addc_u32 s53, s53, 0
	v_cvt_pk_bf16_f32 v156, v30, v34
	v_cvt_pk_bf16_f32 v157, v38, v42
	v_cvt_pk_bf16_f32 v158, v46, v50
	v_cvt_pk_bf16_f32 v159, v54, v58
	v_cvt_pk_bf16_f32 v160, v62, v66
	v_cvt_pk_bf16_f32 v161, v70, v74
	v_cvt_pk_bf16_f32 v162, v78, v82
	v_cvt_pk_bf16_f32 v163, v2, v6
	global_store_dwordx4 v27, v[156:159], s[52:53]
	global_store_dwordx4 v27, v[160:163], s[52:53] offset:16
	s_add_u32 s52, s52, s56
	s_addc_u32 s53, s53, 0
	v_cvt_pk_bf16_f32 v164, v31, v35
	v_cvt_pk_bf16_f32 v165, v39, v43
	v_cvt_pk_bf16_f32 v166, v47, v51
	v_cvt_pk_bf16_f32 v167, v55, v59
	v_cvt_pk_bf16_f32 v168, v63, v67
	v_cvt_pk_bf16_f32 v169, v71, v75
	v_cvt_pk_bf16_f32 v170, v79, v83
	v_cvt_pk_bf16_f32 v171, v3, v7
	global_store_dwordx4 v27, v[164:167], s[52:53]
	global_store_dwordx4 v27, v[168:171], s[52:53] offset:16
	s_add_i32 s6, s6, 1
	s_cmp_ge_u32 s6, 5
	s_cbranch_scc1 .Lwf_drain0
	s_lshl_b32 s7, s6, 8
	s_add_i32 s7, s7, s92
	s_addk_i32 s7, 0x40
	s_mov_b32 s30, 2
	s_cmpk_ge_i32 s7, 0xc0
	s_cselect_b32 s30, 3, s30
	s_cmpk_ge_i32 s7, 0x140
	s_cselect_b32 s30, 4, s30
	s_cmpk_ge_i32 s7, 0x1c0
	s_cselect_b32 s30, 5, s30
	s_cmpk_ge_i32 s7, 0x240
	s_cselect_b32 s30, 6, s30
	s_cmpk_ge_i32 s7, 0x2c0
	s_cselect_b32 s30, 7, s30
	s_cmpk_ge_i32 s7, 0x340
	s_cselect_b32 s30, 8, s30
	s_cmpk_ge_i32 s7, 0x3c0
	s_cselect_b32 s30, 9, s30
	s_cmpk_ge_i32 s7, 0x440
	s_cselect_b32 s30, 10, s30
	s_cmpk_ge_i32 s7, 0x4a0
	s_cselect_b32 s30, 11, s30
	s_cmpk_ge_i32 s7, 0x500
	s_cselect_b32 s30, 12, s30
	s_cmpk_ge_i32 s7, 0x520
	s_cselect_b32 s30, 13, s30
	s_mul_i32 s59, s30, 48
	s_add_u32 s10, s0, s59
	s_addc_u32 s11, s1, 0
	s_load_dwordx2 s[50:51], s[10:11], 0x100
	s_load_dwordx2 s[52:53], s[10:11], 0x110
	s_load_dwordx2 s[90:91], s[10:11], 0x118
	s_load_dword s30, s[10:11], 0x128
	s_load_dwordx2 vcc, s[0:1], 0xf8
	s_waitcnt lgkmcnt(0)
	s_lshr_b32 s30, s30, 2
	s_sub_i32 s7, s7, s30
	s_lshr_b32 s59, s90, 7
	s_add_i32 s10, s59, -1
	s_and_b32 s10, s7, s10
	s_ff1_i32_b32 s59, s59
	s_lshr_b32 s7, s7, s59
	s_lshl_b32 s10, s10, 7
	s_add_i32 s10, s10, s58
	s_lshl_b32 s11, s7, 8
	s_mul_i32 s59, s10, s91
	s_add_i32 s59, s59, s11
	s_lshl_b32 s59, s59, 2
	s_add_u32 s50, s50, s59
	s_addc_u32 s51, s51, 0
	s_mul_i32 s59, s11, s90
	s_add_i32 s59, s59, s10
	s_lshl_b32 s59, s59, 1
	s_add_u32 s52, s52, s59
	s_addc_u32 s53, s53, 0
	s_add_u32 s52, s52, vcc_lo
	s_addc_u32 s53, s53, vcc_hi
	v_mul_u32_u24_e32 v27, s90, v152
	s_lshl_b32 s56, s90, 1
	s_lshl_b32 s91, s91, 2
	global_load_dwordx4 v[28:31], v26, s[50:51] nt
	s_add_u32 s50, s50, s91
	s_addc_u32 s51, s51, 0
	global_load_dwordx4 v[32:35], v26, s[50:51] nt
	s_add_u32 s50, s50, s91
	s_addc_u32 s51, s51, 0
	global_load_dwordx4 v[36:39], v26, s[50:51] nt
	s_add_u32 s50, s50, s91
	s_addc_u32 s51, s51, 0
	global_load_dwordx4 v[40:43], v26, s[50:51] nt
	s_add_u32 s50, s50, s91
	s_addc_u32 s51, s51, 0
	global_load_dwordx4 v[44:47], v26, s[50:51] nt
	s_add_u32 s50, s50, s91
	s_addc_u32 s51, s51, 0
	global_load_dwordx4 v[48:51], v26, s[50:51] nt
	s_add_u32 s50, s50, s91
	s_addc_u32 s51, s51, 0
	global_load_dwordx4 v[52:55], v26, s[50:51] nt
	s_add_u32 s50, s50, s91
	s_addc_u32 s51, s51, 0
	global_load_dwordx4 v[56:59], v26, s[50:51] nt
	s_add_u32 s50, s50, s91
	s_addc_u32 s51, s51, 0
	global_load_dwordx4 v[60:63], v26, s[50:51] nt
	s_add_u32 s50, s50, s91
	s_addc_u32 s51, s51, 0
	global_load_dwordx4 v[64:67], v26, s[50:51] nt
	s_add_u32 s50, s50, s91
	s_addc_u32 s51, s51, 0
	global_load_dwordx4 v[68:71], v26, s[50:51] nt
	s_add_u32 s50, s50, s91
	s_addc_u32 s51, s51, 0
	global_load_dwordx4 v[72:75], v26, s[50:51] nt
	s_add_u32 s50, s50, s91
	s_addc_u32 s51, s51, 0
	global_load_dwordx4 v[76:79], v26, s[50:51] nt
	s_add_u32 s50, s50, s91
	s_addc_u32 s51, s51, 0
	global_load_dwordx4 v[80:83], v26, s[50:51] nt
	s_add_u32 s50, s50, s91
	s_addc_u32 s51, s51, 0
	global_load_dwordx4 v[0:3], v26, s[50:51] nt
	s_add_u32 s50, s50, s91
	s_addc_u32 s51, s51, 0
	global_load_dwordx4 v[4:7], v26, s[50:51] nt
	s_waitcnt vmcnt(16)
	v_cvt_pk_bf16_f32 v156, v86, v90
	v_cvt_pk_bf16_f32 v157, v94, v98
	v_cvt_pk_bf16_f32 v158, v102, v106
	v_cvt_pk_bf16_f32 v159, v110, v114
	v_cvt_pk_bf16_f32 v160, v118, v122
	v_cvt_pk_bf16_f32 v161, v126, v130
	v_cvt_pk_bf16_f32 v162, v134, v140
	v_cvt_pk_bf16_f32 v163, v144, v148
	global_store_dwordx4 v24, v[156:159], s[54:55]
	global_store_dwordx4 v24, v[160:163], s[54:55] offset:16
	s_add_u32 s54, s54, s57
	s_addc_u32 s55, s55, 0
	v_cvt_pk_bf16_f32 v164, v87, v91
	v_cvt_pk_bf16_f32 v165, v95, v99
	v_cvt_pk_bf16_f32 v166, v103, v107
	v_cvt_pk_bf16_f32 v167, v111, v115
	v_cvt_pk_bf16_f32 v168, v119, v123
	v_cvt_pk_bf16_f32 v169, v127, v131
	v_cvt_pk_bf16_f32 v170, v135, v141
	v_cvt_pk_bf16_f32 v171, v145, v149
	global_store_dwordx4 v24, v[164:167], s[54:55]
	global_store_dwordx4 v24, v[168:171], s[54:55] offset:16
	s_add_u32 s54, s54, s57
	s_addc_u32 s55, s55, 0
	v_cvt_pk_bf16_f32 v156, v88, v92
	v_cvt_pk_bf16_f32 v157, v96, v100
	v_cvt_pk_bf16_f32 v158, v104, v108
	v_cvt_pk_bf16_f32 v159, v112, v116
	v_cvt_pk_bf16_f32 v160, v120, v124
	v_cvt_pk_bf16_f32 v161, v128, v132
	v_cvt_pk_bf16_f32 v162, v136, v142
	v_cvt_pk_bf16_f32 v163, v146, v150
	global_store_dwordx4 v24, v[156:159], s[54:55]
	global_store_dwordx4 v24, v[160:163], s[54:55] offset:16
	s_add_u32 s54, s54, s57
	s_addc_u32 s55, s55, 0
	v_cvt_pk_bf16_f32 v164, v89, v93
	v_cvt_pk_bf16_f32 v165, v97, v101
	v_cvt_pk_bf16_f32 v166, v105, v109
	v_cvt_pk_bf16_f32 v167, v113, v117
	v_cvt_pk_bf16_f32 v168, v121, v125
	v_cvt_pk_bf16_f32 v169, v129, v133
	v_cvt_pk_bf16_f32 v170, v137, v143
	v_cvt_pk_bf16_f32 v171, v147, v151
	global_store_dwordx4 v24, v[164:167], s[54:55]
	global_store_dwordx4 v24, v[168:171], s[54:55] offset:16
	s_add_i32 s6, s6, 1
	s_cmp_ge_u32 s6, 5
	s_cbranch_scc1 .Lwf_drain1
	s_lshl_b32 s7, s6, 8
	s_add_i32 s7, s7, s92
	s_addk_i32 s7, 0x40
	s_mov_b32 s30, 2
	s_cmpk_ge_i32 s7, 0xc0
	s_cselect_b32 s30, 3, s30
	s_cmpk_ge_i32 s7, 0x140
	s_cselect_b32 s30, 4, s30
	s_cmpk_ge_i32 s7, 0x1c0
	s_cselect_b32 s30, 5, s30
	s_cmpk_ge_i32 s7, 0x240
	s_cselect_b32 s30, 6, s30
	s_cmpk_ge_i32 s7, 0x2c0
	s_cselect_b32 s30, 7, s30
	s_cmpk_ge_i32 s7, 0x340
	s_cselect_b32 s30, 8, s30
	s_cmpk_ge_i32 s7, 0x3c0
	s_cselect_b32 s30, 9, s30
	s_cmpk_ge_i32 s7, 0x440
	s_cselect_b32 s30, 10, s30
	s_cmpk_ge_i32 s7, 0x4a0
	s_cselect_b32 s30, 11, s30
	s_cmpk_ge_i32 s7, 0x500
	s_cselect_b32 s30, 12, s30
	s_cmpk_ge_i32 s7, 0x520
	s_cselect_b32 s30, 13, s30
	s_mul_i32 s59, s30, 48
	s_add_u32 s10, s0, s59
	s_addc_u32 s11, s1, 0
	s_load_dwordx2 s[50:51], s[10:11], 0x100
	s_load_dwordx2 s[54:55], s[10:11], 0x110
	s_load_dwordx2 s[90:91], s[10:11], 0x118
	s_load_dword s30, s[10:11], 0x128
	s_load_dwordx2 vcc, s[0:1], 0xf8
	s_waitcnt lgkmcnt(0)
	s_lshr_b32 s30, s30, 2
	s_sub_i32 s7, s7, s30
	s_lshr_b32 s59, s90, 7
	s_add_i32 s10, s59, -1
	s_and_b32 s10, s7, s10
	s_ff1_i32_b32 s59, s59
	s_lshr_b32 s7, s7, s59
	s_lshl_b32 s10, s10, 7
	s_add_i32 s10, s10, s58
	s_lshl_b32 s11, s7, 8
	s_mul_i32 s59, s10, s91
	s_add_i32 s59, s59, s11
	s_lshl_b32 s59, s59, 2
	s_add_u32 s50, s50, s59
	s_addc_u32 s51, s51, 0
	s_mul_i32 s59, s11, s90
	s_add_i32 s59, s59, s10
	s_lshl_b32 s59, s59, 1
	s_add_u32 s54, s54, s59
	s_addc_u32 s55, s55, 0
	s_add_u32 s54, s54, vcc_lo
	s_addc_u32 s55, s55, vcc_hi
	v_mul_u32_u24_e32 v24, s90, v152
	s_lshl_b32 s57, s90, 1
	s_lshl_b32 s91, s91, 2
	global_load_dwordx4 v[86:89], v26, s[50:51] nt
	s_add_u32 s50, s50, s91
	s_addc_u32 s51, s51, 0
	global_load_dwordx4 v[90:93], v26, s[50:51] nt
	s_add_u32 s50, s50, s91
	s_addc_u32 s51, s51, 0
	global_load_dwordx4 v[94:97], v26, s[50:51] nt
	s_add_u32 s50, s50, s91
	s_addc_u32 s51, s51, 0
	global_load_dwordx4 v[98:101], v26, s[50:51] nt
	s_add_u32 s50, s50, s91
	s_addc_u32 s51, s51, 0
	global_load_dwordx4 v[102:105], v26, s[50:51] nt
	s_add_u32 s50, s50, s91
	s_addc_u32 s51, s51, 0
	global_load_dwordx4 v[106:109], v26, s[50:51] nt
	s_add_u32 s50, s50, s91
	s_addc_u32 s51, s51, 0
	global_load_dwordx4 v[110:113], v26, s[50:51] nt
	s_add_u32 s50, s50, s91
	s_addc_u32 s51, s51, 0
	global_load_dwordx4 v[114:117], v26, s[50:51] nt
	s_add_u32 s50, s50, s91
	s_addc_u32 s51, s51, 0
	global_load_dwordx4 v[118:121], v26, s[50:51] nt
	s_add_u32 s50, s50, s91
	s_addc_u32 s51, s51, 0
	global_load_dwordx4 v[122:125], v26, s[50:51] nt
	s_add_u32 s50, s50, s91
	s_addc_u32 s51, s51, 0
	global_load_dwordx4 v[126:129], v26, s[50:51] nt
	s_add_u32 s50, s50, s91
	s_addc_u32 s51, s51, 0
	global_load_dwordx4 v[130:133], v26, s[50:51] nt
	s_add_u32 s50, s50, s91
	s_addc_u32 s51, s51, 0
	global_load_dwordx4 v[134:137], v26, s[50:51] nt
	s_add_u32 s50, s50, s91
	s_addc_u32 s51, s51, 0
	global_load_dwordx4 v[140:143], v26, s[50:51] nt
	s_add_u32 s50, s50, s91
	s_addc_u32 s51, s51, 0
	global_load_dwordx4 v[144:147], v26, s[50:51] nt
	s_add_u32 s50, s50, s91
	s_addc_u32 s51, s51, 0
	global_load_dwordx4 v[148:151], v26, s[50:51] nt
	s_branch .Lwf_loop
.Lwf_drain0:
	s_waitcnt vmcnt(0)
	v_cvt_pk_bf16_f32 v156, v86, v90
	v_cvt_pk_bf16_f32 v157, v94, v98
	v_cvt_pk_bf16_f32 v158, v102, v106
	v_cvt_pk_bf16_f32 v159, v110, v114
	v_cvt_pk_bf16_f32 v160, v118, v122
	v_cvt_pk_bf16_f32 v161, v126, v130
	v_cvt_pk_bf16_f32 v162, v134, v140
	v_cvt_pk_bf16_f32 v163, v144, v148
	global_store_dwordx4 v24, v[156:159], s[54:55]
	global_store_dwordx4 v24, v[160:163], s[54:55] offset:16
	s_add_u32 s54, s54, s57
	s_addc_u32 s55, s55, 0
	v_cvt_pk_bf16_f32 v164, v87, v91
	v_cvt_pk_bf16_f32 v165, v95, v99
	v_cvt_pk_bf16_f32 v166, v103, v107
	v_cvt_pk_bf16_f32 v167, v111, v115
	v_cvt_pk_bf16_f32 v168, v119, v123
	v_cvt_pk_bf16_f32 v169, v127, v131
	v_cvt_pk_bf16_f32 v170, v135, v141
	v_cvt_pk_bf16_f32 v171, v145, v149
	global_store_dwordx4 v24, v[164:167], s[54:55]
	global_store_dwordx4 v24, v[168:171], s[54:55] offset:16
	s_add_u32 s54, s54, s57
	s_addc_u32 s55, s55, 0
	v_cvt_pk_bf16_f32 v156, v88, v92
	v_cvt_pk_bf16_f32 v157, v96, v100
	v_cvt_pk_bf16_f32 v158, v104, v108
	v_cvt_pk_bf16_f32 v159, v112, v116
	v_cvt_pk_bf16_f32 v160, v120, v124
	v_cvt_pk_bf16_f32 v161, v128, v132
	v_cvt_pk_bf16_f32 v162, v136, v142
	v_cvt_pk_bf16_f32 v163, v146, v150
	global_store_dwordx4 v24, v[156:159], s[54:55]
	global_store_dwordx4 v24, v[160:163], s[54:55] offset:16
	s_add_u32 s54, s54, s57
	s_addc_u32 s55, s55, 0
	v_cvt_pk_bf16_f32 v164, v89, v93
	v_cvt_pk_bf16_f32 v165, v97, v101
	v_cvt_pk_bf16_f32 v166, v105, v109
	v_cvt_pk_bf16_f32 v167, v113, v117
	v_cvt_pk_bf16_f32 v168, v121, v125
	v_cvt_pk_bf16_f32 v169, v129, v133
	v_cvt_pk_bf16_f32 v170, v137, v143
	v_cvt_pk_bf16_f32 v171, v147, v151
	global_store_dwordx4 v24, v[164:167], s[54:55]
	global_store_dwordx4 v24, v[168:171], s[54:55] offset:16
	s_branch .Lwf_done
.Lwf_drain1:
	s_waitcnt vmcnt(0)
	v_cvt_pk_bf16_f32 v156, v28, v32
	v_cvt_pk_bf16_f32 v157, v36, v40
	v_cvt_pk_bf16_f32 v158, v44, v48
	v_cvt_pk_bf16_f32 v159, v52, v56
	v_cvt_pk_bf16_f32 v160, v60, v64
	v_cvt_pk_bf16_f32 v161, v68, v72
	v_cvt_pk_bf16_f32 v162, v76, v80
	v_cvt_pk_bf16_f32 v163, v0, v4
	global_store_dwordx4 v27, v[156:159], s[52:53]
	global_store_dwordx4 v27, v[160:163], s[52:53] offset:16
	s_add_u32 s52, s52, s56
	s_addc_u32 s53, s53, 0
	v_cvt_pk_bf16_f32 v164, v29, v33
	v_cvt_pk_bf16_f32 v165, v37, v41
	v_cvt_pk_bf16_f32 v166, v45, v49
	v_cvt_pk_bf16_f32 v167, v53, v57
	v_cvt_pk_bf16_f32 v168, v61, v65
	v_cvt_pk_bf16_f32 v169, v69, v73
	v_cvt_pk_bf16_f32 v170, v77, v81
	v_cvt_pk_bf16_f32 v171, v1, v5
	global_store_dwordx4 v27, v[164:167], s[52:53]
	global_store_dwordx4 v27, v[168:171], s[52:53] offset:16
	s_add_u32 s52, s52, s56
	s_addc_u32 s53, s53, 0
	v_cvt_pk_bf16_f32 v156, v30, v34
	v_cvt_pk_bf16_f32 v157, v38, v42
	v_cvt_pk_bf16_f32 v158, v46, v50
	v_cvt_pk_bf16_f32 v159, v54, v58
	v_cvt_pk_bf16_f32 v160, v62, v66
	v_cvt_pk_bf16_f32 v161, v70, v74
	v_cvt_pk_bf16_f32 v162, v78, v82
	v_cvt_pk_bf16_f32 v163, v2, v6
	global_store_dwordx4 v27, v[156:159], s[52:53]
	global_store_dwordx4 v27, v[160:163], s[52:53] offset:16
	s_add_u32 s52, s52, s56
	s_addc_u32 s53, s53, 0
	v_cvt_pk_bf16_f32 v164, v31, v35
	v_cvt_pk_bf16_f32 v165, v39, v43
	v_cvt_pk_bf16_f32 v166, v47, v51
	v_cvt_pk_bf16_f32 v167, v55, v59
	v_cvt_pk_bf16_f32 v168, v63, v67
	v_cvt_pk_bf16_f32 v169, v71, v75
	v_cvt_pk_bf16_f32 v170, v79, v83
	v_cvt_pk_bf16_f32 v171, v3, v7
	global_store_dwordx4 v27, v[164:167], s[52:53]
	global_store_dwordx4 v27, v[168:171], s[52:53] offset:16
	s_branch .Lwf_done
.Lwf_pdrain1:
	s_waitcnt vmcnt(0)
	v_cvt_pk_bf16_f32 v156, v28, v32
	v_cvt_pk_bf16_f32 v157, v36, v40
	v_cvt_pk_bf16_f32 v158, v44, v48
	v_cvt_pk_bf16_f32 v159, v52, v56
	v_cvt_pk_bf16_f32 v160, v60, v64
	v_cvt_pk_bf16_f32 v161, v68, v72
	v_cvt_pk_bf16_f32 v162, v76, v80
	v_cvt_pk_bf16_f32 v163, v0, v4
	global_store_dwordx4 v27, v[156:159], s[52:53]
	global_store_dwordx4 v27, v[160:163], s[52:53] offset:16
	s_add_u32 s52, s52, s56
	s_addc_u32 s53, s53, 0
	v_cvt_pk_bf16_f32 v164, v29, v33
	v_cvt_pk_bf16_f32 v165, v37, v41
	v_cvt_pk_bf16_f32 v166, v45, v49
	v_cvt_pk_bf16_f32 v167, v53, v57
	v_cvt_pk_bf16_f32 v168, v61, v65
	v_cvt_pk_bf16_f32 v169, v69, v73
	v_cvt_pk_bf16_f32 v170, v77, v81
	v_cvt_pk_bf16_f32 v171, v1, v5
	global_store_dwordx4 v27, v[164:167], s[52:53]
	global_store_dwordx4 v27, v[168:171], s[52:53] offset:16
	s_add_u32 s52, s52, s56
	s_addc_u32 s53, s53, 0
	v_cvt_pk_bf16_f32 v156, v30, v34
	v_cvt_pk_bf16_f32 v157, v38, v42
	v_cvt_pk_bf16_f32 v158, v46, v50
	v_cvt_pk_bf16_f32 v159, v54, v58
	v_cvt_pk_bf16_f32 v160, v62, v66
	v_cvt_pk_bf16_f32 v161, v70, v74
	v_cvt_pk_bf16_f32 v162, v78, v82
	v_cvt_pk_bf16_f32 v163, v2, v6
	global_store_dwordx4 v27, v[156:159], s[52:53]
	global_store_dwordx4 v27, v[160:163], s[52:53] offset:16
	s_add_u32 s52, s52, s56
	s_addc_u32 s53, s53, 0
	v_cvt_pk_bf16_f32 v164, v31, v35
	v_cvt_pk_bf16_f32 v165, v39, v43
	v_cvt_pk_bf16_f32 v166, v47, v51
	v_cvt_pk_bf16_f32 v167, v55, v59
	v_cvt_pk_bf16_f32 v168, v63, v67
	v_cvt_pk_bf16_f32 v169, v71, v75
	v_cvt_pk_bf16_f32 v170, v79, v83
	v_cvt_pk_bf16_f32 v171, v3, v7
	global_store_dwordx4 v27, v[164:167], s[52:53]
	global_store_dwordx4 v27, v[168:171], s[52:53] offset:16
